# qkv projection epilogue: Q/K store pairs exchanged between lane halves (DPP row_ror:8 on data and addresses) so each store writes eight full 128-byte head rows instead of thirty-two 32-byte runs
# baseline (speedup 1.0000x reference)
; #define LAS __attribute__((address_space(3)))
; DI float shx(float v, int m, int lane) { return __builtin_bit_cast(float, __builtin_amdgcn_ds_bpermute((lane ^ m) << 2, __builtin_bit_cast(int, v))); }
;     DI void operator()(const Acc& acc, const Unit& u, int wr, int wc, int fr, int fq) const {
;     ...
;                     const int rl = ai * HALF + wr * 64 + m * 16 + fr, r = rowb + rl;
;                     float ss = 0.f;
; #pragma unroll
;                     for (int bj = 0; bj < 2; ++bj)
; #pragma unroll
;                         for (int n = 0; n < 2; ++n) { const f32x4 a = acc[ai][bj][m][n]; ss += a[0] * a[0] + a[1] * a[1] + a[2] * a[2] + a[3] * a[3]; }
;                     ss += shx(ss, 16, 16 * fq + fr); ss += shx(ss, 32, 16 * fq + fr);
;                     const float rstd = rsqrtf(ss * (1.f / 64.f) + LN_EPS);
;                     f32x4 v[2][2];
; #pragma unroll
;                     for (int bj = 0; bj < 2; ++bj)
; #pragma unroll
;                         for (int n = 0; n < 2; ++n) v[bj][n] = acc[ai][bj][m][n] * rstd * g[bj][n];
;                     if (latent) {
;                         const int s = s0 + rl, pos = (fq >> 1) ? (s & 63) : (s >> 6);
; #pragma unroll
;                         for (int n = 0; n < 2; ++n) {
;                             const LAS float* tp = tab + (pos * 16 + 8 * (fq & 1) + 4 * n) * 2;
;                             const f32x4 t0 = *(const LAS f32x4*)tp, t1 = *(const LAS f32x4*)(tp + 4);
;                             const f32x4 cs = {t0[0], t0[2], t1[0], t1[2]}, sn = {t0[1], t0[3], t1[1], t1[3]};
;                             const f32x4 x1 = v[0][n], x2 = v[1][n];
;                             v[0][n] = x1 * cs - x2 * sn; v[1][n] = x2 * cs + x1 * sn;
;                         }
;                     }
; #pragma unroll
;                     for (int bj = 0; bj < 2; ++bj) {
;                         u32x4 o; o[0] = pk_bf16(v[bj][0][0], v[bj][0][1]); o[1] = pk_bf16(v[bj][0][2], v[bj][0][3]); o[2] = pk_bf16(v[bj][1][0], v[bj][1][1]); o[3] = pk_bf16(v[bj][1][2], v[bj][1][3]);
;                         bf16_t* dst = tile < 4 ? Q + (size_t)r * 1024 + (tile * 4 + wc) * 64 + dbase + 16 * bj
;                                                : Kd + ((size_t)(b * 4 + wc) * NKEY + kp0 + rl) * 64 + dbase + 16 * bj;
;                         *(u32x4*)dst = o;
.LBB0_754:
	s_lshl_b32 s21, s21, 8
	v_readlane_b32 s24, v255, 26
	s_or_b32 s58, s21, s24
	s_lshl_b32 s21, s23, 2
	s_or_b32 s21, s21, s38
	s_ashr_i32 s59, s58, 31
	s_mul_hi_i32 s23, s21, 0x900
	s_mulk_i32 s21, 0x900
	s_add_u32 s60, s21, s22
	v_add_u32_e32 v170, s19, v148
	s_addc_u32 s61, s23, 0
	v_ashrrev_i32_e32 v171, 31, v170
	v_readlane_b32 s22, v254, 27
	v_lshlrev_b64 v[170:171], 11, v[170:171]
	v_lshl_add_u64 v[172:173], s[60:61], 0, v[148:149]
	v_readlane_b32 s23, v254, 28
	v_lshlrev_b64 v[172:173], 7, v[172:173]
	v_cvt_pk_bf16_f32 v140, v140, v141
	v_cvt_pk_bf16_f32 v141, v142, v143
	v_cvt_pk_bf16_f32 v142, v136, v137
	v_lshl_add_u64 v[136:137], s[22:23], 0, v[170:171]
	v_cvt_pk_bf16_f32 v143, v138, v139
	v_lshl_add_u64 v[136:137], s[58:59], 1, v[136:137]
	v_lshl_add_u64 v[138:139], s[26:27], 0, v[172:173]
	v_cndmask_b32_e64 v137, v137, v139, s[2:3]
	v_cndmask_b32_e64 v136, v136, v138, s[2:3]
	v_lshl_add_u64 v[138:139], v[136:137], 0, v[168:169]
	v_cvt_pk_bf16_f32 v136, v130, v131
	v_mov_b32_e32 v130, v121
	v_mov_b32_e32 v131, v125
	v_cvt_pk_bf16_f32 v137, v128, v129
	v_mov_b32_e32 v128, v120
	v_mov_b32_e32 v129, v124
	v_pk_mul_f32 v[130:131], v[130:131], v[130:131]
	v_cvt_pk_bf16_f32 v134, v134, v135
	v_pk_fma_f32 v[128:129], v[128:129], v[128:129], v[130:131]
	v_mov_b32_e32 v130, v122
	v_mov_b32_e32 v131, v126
	v_cvt_pk_bf16_f32 v135, v132, v133
	v_pk_fma_f32 v[128:129], v[130:131], v[130:131], v[128:129]
	v_mov_b32_e32 v130, v123
	v_mov_b32_e32 v131, v127
	v_mov_b32_e32 v132, v113
	v_mov_b32_e32 v133, v117
	v_pk_fma_f32 v[128:129], v[130:131], v[130:131], v[128:129]
	v_mov_b32_e32 v130, v112
	v_mov_b32_e32 v131, v116
	v_pk_mul_f32 v[132:133], v[132:133], v[132:133]
	v_add_f32_e32 v128, v128, v129
	v_pk_fma_f32 v[130:131], v[130:131], v[130:131], v[132:133]
	v_mov_b32_e32 v132, v114
	v_mov_b32_e32 v133, v118
	v_pk_fma_f32 v[130:131], v[132:133], v[132:133], v[130:131]
	v_mov_b32_e32 v132, v115
	v_mov_b32_e32 v133, v119
	v_pk_fma_f32 v[130:131], v[132:133], v[132:133], v[130:131]
	s_mov_b32 s21, 0x800000
	v_add_f32_e32 v128, v131, v128
	v_add_f32_e32 v128, v130, v128
	ds_bpermute_b32 v129, v180, v128
	s_mov_b64 s[36:37], s[52:53]
	s_mov_b64 s[42:43], s[16:17]
	s_nop 1
	v_mov_b32_dpp v202, v138 row_ror:8 row_mask:0xf bank_mask:0xf
	v_mov_b32_dpp v203, v139 row_ror:8 row_mask:0xf bank_mask:0xf
	v_mov_b32_e32 v210, 32
	v_mov_b32_e32 v211, 0
	v_mov_b32_e32 v206, v138
	v_mov_b32_e32 v207, v139
	v_lshl_add_u64 v[208:209], v[138:139], 0, v[210:211]
	v_lshl_add_u64 v[204:205], v[202:203], 0, v[210:211]
	v_mov_b32_dpp v212, v140 row_ror:8 row_mask:0xf bank_mask:0x3
	v_mov_b32_dpp v213, v141 row_ror:8 row_mask:0xf bank_mask:0x3
	v_mov_b32_dpp v214, v142 row_ror:8 row_mask:0xf bank_mask:0x3
	v_mov_b32_dpp v215, v143 row_ror:8 row_mask:0xf bank_mask:0x3
	v_mov_b32_dpp v206, v204 quad_perm:[0,1,2,3] row_mask:0xf bank_mask:0xc
	v_mov_b32_dpp v207, v205 quad_perm:[0,1,2,3] row_mask:0xf bank_mask:0xc
	v_mov_b32_dpp v208, v202 quad_perm:[0,1,2,3] row_mask:0xf bank_mask:0x3
	v_mov_b32_dpp v209, v203 quad_perm:[0,1,2,3] row_mask:0xf bank_mask:0x3
	v_mov_b32_dpp v140, v134 row_ror:8 row_mask:0xf bank_mask:0xc
	v_mov_b32_dpp v141, v135 row_ror:8 row_mask:0xf bank_mask:0xc
	v_mov_b32_dpp v142, v136 row_ror:8 row_mask:0xf bank_mask:0xc
	v_mov_b32_dpp v143, v137 row_ror:8 row_mask:0xf bank_mask:0xc
	v_mov_b32_dpp v134, v212 quad_perm:[0,1,2,3] row_mask:0xf bank_mask:0x3
	v_mov_b32_dpp v135, v213 quad_perm:[0,1,2,3] row_mask:0xf bank_mask:0x3
	v_mov_b32_dpp v136, v214 quad_perm:[0,1,2,3] row_mask:0xf bank_mask:0x3
	v_mov_b32_dpp v137, v215 quad_perm:[0,1,2,3] row_mask:0xf bank_mask:0x3
	global_store_dwordx4 v[206:207], v[140:143], off
	global_store_dwordx4 v[208:209], v[134:137], off
	s_nop 1
	s_waitcnt lgkmcnt(0)
	v_add_f32_e32 v128, v128, v129
	ds_bpermute_b32 v129, v181, v128
	s_waitcnt lgkmcnt(0)
	v_add_f32_e32 v128, v128, v129
	v_fmamk_f32 v128, v128, 0x3c800000, v250
	v_cmp_gt_f32_e32 vcc, s21, v128
	v_mul_f32_e32 v129, 0x4b800000, v128
	s_nop 0
	v_cndmask_b32_e32 v128, v128, v129, vcc
	v_rsq_f32_e32 v128, v128
	s_nop 0
	v_mul_f32_e32 v129, 0x45800000, v128
	v_cndmask_b32_e32 v128, v128, v129, vcc
	v_pk_mul_f32 v[130:131], v[116:117], v[128:129] op_sel_hi:[1,0]
	v_pk_mul_f32 v[124:125], v[124:125], v[128:129] op_sel_hi:[1,0]
	v_pk_mul_f32 v[126:127], v[126:127], v[128:129] op_sel_hi:[1,0]
	v_pk_mul_f32 v[120:121], v[120:121], v[128:129] op_sel_hi:[1,0]
	v_pk_mul_f32 v[122:123], v[122:123], v[128:129] op_sel_hi:[1,0]
	v_pk_mul_f32 v[116:117], v[118:119], v[128:129] op_sel_hi:[1,0]
	v_pk_mul_f32 v[118:119], v[72:73], v[130:131]
	v_pk_mul_f32 v[130:131], v[112:113], v[128:129] op_sel_hi:[1,0]
	v_pk_mul_f32 v[112:113], v[114:115], v[128:129] op_sel_hi:[1,0]
	v_pk_mul_f32 v[126:127], v[78:79], v[126:127]
	v_pk_mul_f32 v[124:125], v[76:77], v[124:125]
	v_pk_mul_f32 v[122:123], v[70:71], v[122:123]
	v_pk_mul_f32 v[120:121], v[68:69], v[120:121]
	v_pk_mul_f32 v[116:117], v[74:75], v[116:117]
	v_pk_mul_f32 v[112:113], v[66:67], v[112:113]
	v_pk_mul_f32 v[114:115], v[64:65], v[130:131]
	s_and_b64 vcc, exec, s[4:5]
	s_cbranch_vccnz .LBB0_756
	s_add_i32 s21, s20, s39
	s_lshr_b32 s21, s21, 6
	v_mov_b32_e32 v128, s21
	v_cndmask_b32_e64 v128, v182, v128, s[44:45]
	v_lshlrev_b32_e32 v170, 7, v128
	v_add_u32_e32 v132, v185, v170
	ds_read_b128 v[128:131], v132
	ds_read_b128 v[132:135], v132 offset:16
	s_waitcnt lgkmcnt(1)
	v_mov_b32_e32 v138, v129
	v_mov_b32_e32 v139, v131
	v_pk_mul_f32 v[140:141], v[118:119], v[138:139]
	s_waitcnt lgkmcnt(0)
	v_mov_b32_e32 v142, v133
	v_mov_b32_e32 v143, v135
	v_mov_b32_e32 v133, v134
	v_mov_b32_e32 v129, v130
	v_pk_mul_f32 v[136:137], v[116:117], v[142:143]
	v_pk_fma_f32 v[134:135], v[124:125], v[128:129], v[140:141] neg_lo:[0,0,1] neg_hi:[0,0,1]
	v_pk_mul_f32 v[118:119], v[118:119], v[128:129]
	v_pk_mul_f32 v[116:117], v[116:117], v[132:133]
	v_add_u32_e32 v128, v186, v170
	v_pk_fma_f32 v[136:137], v[126:127], v[132:133], v[136:137] neg_lo:[0,0,1] neg_hi:[0,0,1]
	v_pk_fma_f32 v[116:117], v[126:127], v[142:143], v[116:117]
	v_pk_fma_f32 v[118:119], v[124:125], v[138:139], v[118:119]
	ds_read_b128 v[124:127], v128
	ds_read_b128 v[128:131], v128 offset:16
	s_waitcnt lgkmcnt(1)
	v_mov_b32_e32 v138, v125
	v_mov_b32_e32 v139, v127
	v_pk_mul_f32 v[140:141], v[114:115], v[138:139]
	s_waitcnt lgkmcnt(0)
	v_mov_b32_e32 v142, v129
	v_mov_b32_e32 v143, v131
	v_mov_b32_e32 v129, v130
	v_mov_b32_e32 v125, v126
	v_pk_mul_f32 v[132:133], v[112:113], v[142:143]
	v_pk_fma_f32 v[130:131], v[120:121], v[124:125], v[140:141] neg_lo:[0,0,1] neg_hi:[0,0,1]
	v_pk_mul_f32 v[114:115], v[114:115], v[124:125]
	v_pk_mul_f32 v[112:113], v[112:113], v[128:129]
	v_pk_fma_f32 v[132:133], v[122:123], v[128:129], v[132:133] neg_lo:[0,0,1] neg_hi:[0,0,1]
	v_pk_fma_f32 v[112:113], v[122:123], v[142:143], v[112:113]
	v_pk_fma_f32 v[114:115], v[120:121], v[138:139], v[114:115]
	v_mov_b64_e32 v[120:121], v[130:131]
	v_mov_b64_e32 v[124:125], v[134:135]
	v_mov_b64_e32 v[122:123], v[132:133]
	v_mov_b64_e32 v[126:127], v[136:137]
; #define LAS __attribute__((address_space(3)))
; DI float shx(float v, int m, int lane) { return __builtin_bit_cast(float, __builtin_amdgcn_ds_bpermute((lane ^ m) << 2, __builtin_bit_cast(int, v))); }
;     DI void operator()(const Acc& acc, const Unit& u, int wr, int wc, int fr, int fq) const {
;     ...
;                     const int rl = ai * HALF + wr * 64 + m * 16 + fr, r = rowb + rl;
;                     float ss = 0.f;
; #pragma unroll
;                     for (int bj = 0; bj < 2; ++bj)
; #pragma unroll
;                         for (int n = 0; n < 2; ++n) { const f32x4 a = acc[ai][bj][m][n]; ss += a[0] * a[0] + a[1] * a[1] + a[2] * a[2] + a[3] * a[3]; }
;                     ss += shx(ss, 16, 16 * fq + fr); ss += shx(ss, 32, 16 * fq + fr);
;                     const float rstd = rsqrtf(ss * (1.f / 64.f) + LN_EPS);
;                     f32x4 v[2][2];
; #pragma unroll
;                     for (int bj = 0; bj < 2; ++bj)
; #pragma unroll
;                         for (int n = 0; n < 2; ++n) v[bj][n] = acc[ai][bj][m][n] * rstd * g[bj][n];
;                     if (latent) {
;                         const int s = s0 + rl, pos = (fq >> 1) ? (s & 63) : (s >> 6);
; #pragma unroll
;                         for (int n = 0; n < 2; ++n) {
;                             const LAS float* tp = tab + (pos * 16 + 8 * (fq & 1) + 4 * n) * 2;
;                             const f32x4 t0 = *(const LAS f32x4*)tp, t1 = *(const LAS f32x4*)(tp + 4);
;                             const f32x4 cs = {t0[0], t0[2], t1[0], t1[2]}, sn = {t0[1], t0[3], t1[1], t1[3]};
;                             const f32x4 x1 = v[0][n], x2 = v[1][n];
;                             v[0][n] = x1 * cs - x2 * sn; v[1][n] = x2 * cs + x1 * sn;
;                         }
;                     }
; #pragma unroll
;                     for (int bj = 0; bj < 2; ++bj) {
;                         u32x4 o; o[0] = pk_bf16(v[bj][0][0], v[bj][0][1]); o[1] = pk_bf16(v[bj][0][2], v[bj][0][3]); o[2] = pk_bf16(v[bj][1][0], v[bj][1][1]); o[3] = pk_bf16(v[bj][1][2], v[bj][1][3]);
;                         bf16_t* dst = tile < 4 ? Q + (size_t)r * 1024 + (tile * 4 + wc) * 64 + dbase + 16 * bj
;                                                : Kd + ((size_t)(b * 4 + wc) * NKEY + kp0 + rl) * 64 + dbase + 16 * bj;
;                         *(u32x4*)dst = o;
;                     }
.LBB0_756:
	v_add_u32_e32 v128, s19, v152
	v_ashrrev_i32_e32 v129, 31, v128
	v_readlane_b32 s22, v254, 27
	v_lshlrev_b64 v[128:129], 11, v[128:129]
	v_lshl_add_u64 v[130:131], s[60:61], 0, v[152:153]
	v_readlane_b32 s23, v254, 28
	v_lshlrev_b64 v[130:131], 7, v[130:131]
	v_cvt_pk_bf16_f32 v124, v124, v125
	v_cvt_pk_bf16_f32 v125, v126, v127
	v_cvt_pk_bf16_f32 v126, v120, v121
	v_lshl_add_u64 v[120:121], s[22:23], 0, v[128:129]
	v_cvt_pk_bf16_f32 v127, v122, v123
	v_lshl_add_u64 v[120:121], s[58:59], 1, v[120:121]
	v_lshl_add_u64 v[122:123], s[26:27], 0, v[130:131]
	v_cndmask_b32_e64 v121, v121, v123, s[2:3]
	v_cndmask_b32_e64 v120, v120, v122, s[2:3]
	v_lshl_add_u64 v[122:123], v[120:121], 0, v[168:169]
	v_cvt_pk_bf16_f32 v120, v114, v115
	v_mov_b32_e32 v114, v105
	v_mov_b32_e32 v115, v109
	v_cvt_pk_bf16_f32 v121, v112, v113
	v_mov_b32_e32 v112, v104
	v_mov_b32_e32 v113, v108
	v_pk_mul_f32 v[114:115], v[114:115], v[114:115]
	v_cvt_pk_bf16_f32 v118, v118, v119
	v_pk_fma_f32 v[112:113], v[112:113], v[112:113], v[114:115]
	v_mov_b32_e32 v114, v106
	v_mov_b32_e32 v115, v110
	v_cvt_pk_bf16_f32 v119, v116, v117
	v_pk_fma_f32 v[112:113], v[114:115], v[114:115], v[112:113]
	v_mov_b32_e32 v114, v107
	v_mov_b32_e32 v115, v111
	v_mov_b32_e32 v116, v97
	v_mov_b32_e32 v117, v101
	v_pk_fma_f32 v[112:113], v[114:115], v[114:115], v[112:113]
	v_mov_b32_e32 v114, v96
	v_mov_b32_e32 v115, v100
	v_pk_mul_f32 v[116:117], v[116:117], v[116:117]
	v_add_f32_e32 v112, v112, v113
	v_pk_fma_f32 v[114:115], v[114:115], v[114:115], v[116:117]
	v_mov_b32_e32 v116, v98
	v_mov_b32_e32 v117, v102
	v_pk_fma_f32 v[114:115], v[116:117], v[116:117], v[114:115]
	v_mov_b32_e32 v116, v99
	v_mov_b32_e32 v117, v103
	v_pk_fma_f32 v[114:115], v[116:117], v[116:117], v[114:115]
	s_mov_b32 s21, 0x800000
	v_add_f32_e32 v112, v115, v112
	v_add_f32_e32 v112, v114, v112
	ds_bpermute_b32 v113, v180, v112
	v_readlane_b32 s16, v255, 27
	v_readlane_b32 s17, v255, 28
	s_nop 1
	v_mov_b32_dpp v202, v122 row_ror:8 row_mask:0xf bank_mask:0xf
	v_mov_b32_dpp v203, v123 row_ror:8 row_mask:0xf bank_mask:0xf
	v_mov_b32_e32 v210, 32
	v_mov_b32_e32 v211, 0
	v_mov_b32_e32 v206, v122
	v_mov_b32_e32 v207, v123
	v_lshl_add_u64 v[208:209], v[122:123], 0, v[210:211]
	v_lshl_add_u64 v[204:205], v[202:203], 0, v[210:211]
	v_mov_b32_dpp v212, v124 row_ror:8 row_mask:0xf bank_mask:0x3
	v_mov_b32_dpp v213, v125 row_ror:8 row_mask:0xf bank_mask:0x3
	v_mov_b32_dpp v214, v126 row_ror:8 row_mask:0xf bank_mask:0x3
	v_mov_b32_dpp v215, v127 row_ror:8 row_mask:0xf bank_mask:0x3
	v_mov_b32_dpp v206, v204 quad_perm:[0,1,2,3] row_mask:0xf bank_mask:0xc
	v_mov_b32_dpp v207, v205 quad_perm:[0,1,2,3] row_mask:0xf bank_mask:0xc
	v_mov_b32_dpp v208, v202 quad_perm:[0,1,2,3] row_mask:0xf bank_mask:0x3
	v_mov_b32_dpp v209, v203 quad_perm:[0,1,2,3] row_mask:0xf bank_mask:0x3
	v_mov_b32_dpp v124, v118 row_ror:8 row_mask:0xf bank_mask:0xc
	v_mov_b32_dpp v125, v119 row_ror:8 row_mask:0xf bank_mask:0xc
	v_mov_b32_dpp v126, v120 row_ror:8 row_mask:0xf bank_mask:0xc
	v_mov_b32_dpp v127, v121 row_ror:8 row_mask:0xf bank_mask:0xc
	v_mov_b32_dpp v118, v212 quad_perm:[0,1,2,3] row_mask:0xf bank_mask:0x3
	v_mov_b32_dpp v119, v213 quad_perm:[0,1,2,3] row_mask:0xf bank_mask:0x3
	v_mov_b32_dpp v120, v214 quad_perm:[0,1,2,3] row_mask:0xf bank_mask:0x3
	v_mov_b32_dpp v121, v215 quad_perm:[0,1,2,3] row_mask:0xf bank_mask:0x3
	global_store_dwordx4 v[206:207], v[124:127], off
	global_store_dwordx4 v[208:209], v[118:121], off
	s_nop 1
	s_waitcnt lgkmcnt(0)
	v_add_f32_e32 v112, v112, v113
	ds_bpermute_b32 v113, v181, v112
	s_waitcnt lgkmcnt(0)
	v_add_f32_e32 v112, v112, v113
	v_fmamk_f32 v112, v112, 0x3c800000, v250
	v_cmp_gt_f32_e32 vcc, s21, v112
	v_mul_f32_e32 v113, 0x4b800000, v112
	s_nop 0
	v_cndmask_b32_e32 v112, v112, v113, vcc
	v_rsq_f32_e32 v112, v112
	s_nop 0
	v_mul_f32_e32 v113, 0x45800000, v112
	v_cndmask_b32_e32 v112, v112, v113, vcc
	v_pk_mul_f32 v[114:115], v[100:101], v[112:113] op_sel_hi:[1,0]
	v_pk_mul_f32 v[108:109], v[108:109], v[112:113] op_sel_hi:[1,0]
	v_pk_mul_f32 v[110:111], v[110:111], v[112:113] op_sel_hi:[1,0]
	v_pk_mul_f32 v[104:105], v[104:105], v[112:113] op_sel_hi:[1,0]
	v_pk_mul_f32 v[106:107], v[106:107], v[112:113] op_sel_hi:[1,0]
	v_pk_mul_f32 v[100:101], v[102:103], v[112:113] op_sel_hi:[1,0]
	v_pk_mul_f32 v[102:103], v[72:73], v[114:115]
	v_pk_mul_f32 v[114:115], v[96:97], v[112:113] op_sel_hi:[1,0]
	v_pk_mul_f32 v[96:97], v[98:99], v[112:113] op_sel_hi:[1,0]
	v_pk_mul_f32 v[110:111], v[78:79], v[110:111]
	v_pk_mul_f32 v[108:109], v[76:77], v[108:109]
	v_pk_mul_f32 v[106:107], v[70:71], v[106:107]
	v_pk_mul_f32 v[104:105], v[68:69], v[104:105]
	v_pk_mul_f32 v[100:101], v[74:75], v[100:101]
	v_pk_mul_f32 v[96:97], v[66:67], v[96:97]
	v_pk_mul_f32 v[98:99], v[64:65], v[114:115]
	s_and_b64 vcc, exec, s[4:5]
	s_cbranch_vccnz .LBB0_758
	s_add_i32 s21, s20, s39
	s_lshr_b32 s21, s21, 6
	v_mov_b32_e32 v112, s21
	v_cndmask_b32_e64 v112, v183, v112, s[44:45]
	v_lshlrev_b32_e32 v128, 7, v112
	v_add_u32_e32 v116, v185, v128
	ds_read_b128 v[112:115], v116
	ds_read_b128 v[116:119], v116 offset:16
	s_waitcnt lgkmcnt(1)
	v_mov_b32_e32 v122, v113
	v_mov_b32_e32 v123, v115
	v_pk_mul_f32 v[124:125], v[102:103], v[122:123]
	s_waitcnt lgkmcnt(0)
	v_mov_b32_e32 v126, v117
	v_mov_b32_e32 v127, v119
	v_mov_b32_e32 v117, v118
	v_mov_b32_e32 v113, v114
	v_pk_mul_f32 v[120:121], v[100:101], v[126:127]
	v_pk_fma_f32 v[118:119], v[108:109], v[112:113], v[124:125] neg_lo:[0,0,1] neg_hi:[0,0,1]
	v_pk_mul_f32 v[102:103], v[102:103], v[112:113]
	v_pk_mul_f32 v[100:101], v[100:101], v[116:117]
	v_add_u32_e32 v112, v186, v128
	v_pk_fma_f32 v[120:121], v[110:111], v[116:117], v[120:121] neg_lo:[0,0,1] neg_hi:[0,0,1]
	v_pk_fma_f32 v[100:101], v[110:111], v[126:127], v[100:101]
	v_pk_fma_f32 v[102:103], v[108:109], v[122:123], v[102:103]
	ds_read_b128 v[108:111], v112
	ds_read_b128 v[112:115], v112 offset:16
	s_waitcnt lgkmcnt(1)
	v_mov_b32_e32 v122, v109
	v_mov_b32_e32 v123, v111
	v_pk_mul_f32 v[124:125], v[98:99], v[122:123]
	s_waitcnt lgkmcnt(0)
	v_mov_b32_e32 v126, v113
	v_mov_b32_e32 v127, v115
	v_mov_b32_e32 v113, v114
	v_mov_b32_e32 v109, v110
	v_pk_mul_f32 v[116:117], v[96:97], v[126:127]
	v_pk_fma_f32 v[114:115], v[104:105], v[108:109], v[124:125] neg_lo:[0,0,1] neg_hi:[0,0,1]
	v_pk_mul_f32 v[98:99], v[98:99], v[108:109]
	v_pk_mul_f32 v[96:97], v[96:97], v[112:113]
	v_pk_fma_f32 v[116:117], v[106:107], v[112:113], v[116:117] neg_lo:[0,0,1] neg_hi:[0,0,1]
	v_pk_fma_f32 v[96:97], v[106:107], v[126:127], v[96:97]
	v_pk_fma_f32 v[98:99], v[104:105], v[122:123], v[98:99]
	v_mov_b64_e32 v[104:105], v[114:115]
	v_mov_b64_e32 v[108:109], v[118:119]
	v_mov_b64_e32 v[106:107], v[116:117]
	v_mov_b64_e32 v[110:111], v[120:121]
; #define LAS __attribute__((address_space(3)))
; DI float shx(float v, int m, int lane) { return __builtin_bit_cast(float, __builtin_amdgcn_ds_bpermute((lane ^ m) << 2, __builtin_bit_cast(int, v))); }
;     DI void operator()(const Acc& acc, const Unit& u, int wr, int wc, int fr, int fq) const {
;     ...
;                     const int rl = ai * HALF + wr * 64 + m * 16 + fr, r = rowb + rl;
;                     float ss = 0.f;
; #pragma unroll
;                     for (int bj = 0; bj < 2; ++bj)
; #pragma unroll
;                         for (int n = 0; n < 2; ++n) { const f32x4 a = acc[ai][bj][m][n]; ss += a[0] * a[0] + a[1] * a[1] + a[2] * a[2] + a[3] * a[3]; }
;                     ss += shx(ss, 16, 16 * fq + fr); ss += shx(ss, 32, 16 * fq + fr);
;                     const float rstd = rsqrtf(ss * (1.f / 64.f) + LN_EPS);
;                     f32x4 v[2][2];
; #pragma unroll
;                     for (int bj = 0; bj < 2; ++bj)
; #pragma unroll
;                         for (int n = 0; n < 2; ++n) v[bj][n] = acc[ai][bj][m][n] * rstd * g[bj][n];
;                     if (latent) {
;                         const int s = s0 + rl, pos = (fq >> 1) ? (s & 63) : (s >> 6);
; #pragma unroll
;                         for (int n = 0; n < 2; ++n) {
;                             const LAS float* tp = tab + (pos * 16 + 8 * (fq & 1) + 4 * n) * 2;
;                             const f32x4 t0 = *(const LAS f32x4*)tp, t1 = *(const LAS f32x4*)(tp + 4);
;                             const f32x4 cs = {t0[0], t0[2], t1[0], t1[2]}, sn = {t0[1], t0[3], t1[1], t1[3]};
;                             const f32x4 x1 = v[0][n], x2 = v[1][n];
;                             v[0][n] = x1 * cs - x2 * sn; v[1][n] = x2 * cs + x1 * sn;
;                         }
;                     }
; #pragma unroll
;                     for (int bj = 0; bj < 2; ++bj) {
;                         u32x4 o; o[0] = pk_bf16(v[bj][0][0], v[bj][0][1]); o[1] = pk_bf16(v[bj][0][2], v[bj][0][3]); o[2] = pk_bf16(v[bj][1][0], v[bj][1][1]); o[3] = pk_bf16(v[bj][1][2], v[bj][1][3]);
;                         bf16_t* dst = tile < 4 ? Q + (size_t)r * 1024 + (tile * 4 + wc) * 64 + dbase + 16 * bj
;                                                : Kd + ((size_t)(b * 4 + wc) * NKEY + kp0 + rl) * 64 + dbase + 16 * bj;
;                         *(u32x4*)dst = o;
;                     }
.LBB0_758:
	v_add_u32_e32 v112, s19, v154
	v_ashrrev_i32_e32 v113, 31, v112
	v_readlane_b32 s22, v254, 27
	v_lshlrev_b64 v[112:113], 11, v[112:113]
	v_lshl_add_u64 v[114:115], s[60:61], 0, v[154:155]
	v_readlane_b32 s23, v254, 28
	v_lshlrev_b64 v[114:115], 7, v[114:115]
	v_cvt_pk_bf16_f32 v108, v108, v109
	v_cvt_pk_bf16_f32 v109, v110, v111
	v_cvt_pk_bf16_f32 v110, v104, v105
	v_lshl_add_u64 v[104:105], s[22:23], 0, v[112:113]
	v_cvt_pk_bf16_f32 v111, v106, v107
	v_lshl_add_u64 v[104:105], s[58:59], 1, v[104:105]
	v_lshl_add_u64 v[106:107], s[26:27], 0, v[114:115]
	v_cndmask_b32_e64 v105, v105, v107, s[2:3]
	v_cndmask_b32_e64 v104, v104, v106, s[2:3]
	v_lshl_add_u64 v[106:107], v[104:105], 0, v[168:169]
	v_cvt_pk_bf16_f32 v104, v98, v99
	v_mov_b32_e32 v98, v89
	v_mov_b32_e32 v99, v93
	v_cvt_pk_bf16_f32 v105, v96, v97
	v_mov_b32_e32 v96, v88
	v_mov_b32_e32 v97, v92
	v_pk_mul_f32 v[98:99], v[98:99], v[98:99]
	v_cvt_pk_bf16_f32 v102, v102, v103
	v_pk_fma_f32 v[96:97], v[96:97], v[96:97], v[98:99]
	v_mov_b32_e32 v98, v90
	v_mov_b32_e32 v99, v94
	v_cvt_pk_bf16_f32 v103, v100, v101
	v_pk_fma_f32 v[96:97], v[98:99], v[98:99], v[96:97]
	v_mov_b32_e32 v98, v91
	v_mov_b32_e32 v99, v95
	v_mov_b32_e32 v100, v81
	v_mov_b32_e32 v101, v85
	v_pk_fma_f32 v[96:97], v[98:99], v[98:99], v[96:97]
	v_mov_b32_e32 v98, v80
	v_mov_b32_e32 v99, v84
	v_pk_mul_f32 v[100:101], v[100:101], v[100:101]
	v_add_f32_e32 v96, v96, v97
	v_pk_fma_f32 v[98:99], v[98:99], v[98:99], v[100:101]
	v_mov_b32_e32 v100, v82
	v_mov_b32_e32 v101, v86
	v_pk_fma_f32 v[98:99], v[100:101], v[100:101], v[98:99]
	v_mov_b32_e32 v100, v83
	v_mov_b32_e32 v101, v87
	v_pk_fma_f32 v[98:99], v[100:101], v[100:101], v[98:99]
	s_mov_b32 s21, 0x800000
	v_add_f32_e32 v96, v99, v96
	v_add_f32_e32 v96, v98, v96
	ds_bpermute_b32 v97, v180, v96
	s_nop 1
	v_mov_b32_dpp v202, v106 row_ror:8 row_mask:0xf bank_mask:0xf
	v_mov_b32_dpp v203, v107 row_ror:8 row_mask:0xf bank_mask:0xf
	v_mov_b32_e32 v210, 32
	v_mov_b32_e32 v211, 0
	v_mov_b32_e32 v206, v106
	v_mov_b32_e32 v207, v107
	v_lshl_add_u64 v[208:209], v[106:107], 0, v[210:211]
	v_lshl_add_u64 v[204:205], v[202:203], 0, v[210:211]
	v_mov_b32_dpp v212, v108 row_ror:8 row_mask:0xf bank_mask:0x3
	v_mov_b32_dpp v213, v109 row_ror:8 row_mask:0xf bank_mask:0x3
	v_mov_b32_dpp v214, v110 row_ror:8 row_mask:0xf bank_mask:0x3
	v_mov_b32_dpp v215, v111 row_ror:8 row_mask:0xf bank_mask:0x3
	v_mov_b32_dpp v206, v204 quad_perm:[0,1,2,3] row_mask:0xf bank_mask:0xc
	v_mov_b32_dpp v207, v205 quad_perm:[0,1,2,3] row_mask:0xf bank_mask:0xc
	v_mov_b32_dpp v208, v202 quad_perm:[0,1,2,3] row_mask:0xf bank_mask:0x3
	v_mov_b32_dpp v209, v203 quad_perm:[0,1,2,3] row_mask:0xf bank_mask:0x3
	v_mov_b32_dpp v108, v102 row_ror:8 row_mask:0xf bank_mask:0xc
	v_mov_b32_dpp v109, v103 row_ror:8 row_mask:0xf bank_mask:0xc
	v_mov_b32_dpp v110, v104 row_ror:8 row_mask:0xf bank_mask:0xc
	v_mov_b32_dpp v111, v105 row_ror:8 row_mask:0xf bank_mask:0xc
	v_mov_b32_dpp v102, v212 quad_perm:[0,1,2,3] row_mask:0xf bank_mask:0x3
	v_mov_b32_dpp v103, v213 quad_perm:[0,1,2,3] row_mask:0xf bank_mask:0x3
	v_mov_b32_dpp v104, v214 quad_perm:[0,1,2,3] row_mask:0xf bank_mask:0x3
	v_mov_b32_dpp v105, v215 quad_perm:[0,1,2,3] row_mask:0xf bank_mask:0x3
	global_store_dwordx4 v[206:207], v[108:111], off
	global_store_dwordx4 v[208:209], v[102:105], off
	s_nop 1
	s_waitcnt lgkmcnt(0)
	v_add_f32_e32 v96, v96, v97
	ds_bpermute_b32 v97, v181, v96
	s_waitcnt lgkmcnt(0)
	v_add_f32_e32 v96, v96, v97
	v_fmamk_f32 v96, v96, 0x3c800000, v250
	v_cmp_gt_f32_e32 vcc, s21, v96
	v_mul_f32_e32 v97, 0x4b800000, v96
	s_nop 0
	v_cndmask_b32_e32 v96, v96, v97, vcc
	v_rsq_f32_e32 v96, v96
	s_nop 0
	v_mul_f32_e32 v97, 0x45800000, v96
	v_cndmask_b32_e32 v96, v96, v97, vcc
	v_pk_mul_f32 v[98:99], v[84:85], v[96:97] op_sel_hi:[1,0]
	v_pk_mul_f32 v[92:93], v[92:93], v[96:97] op_sel_hi:[1,0]
	v_pk_mul_f32 v[94:95], v[94:95], v[96:97] op_sel_hi:[1,0]
	v_pk_mul_f32 v[88:89], v[88:89], v[96:97] op_sel_hi:[1,0]
	v_pk_mul_f32 v[90:91], v[90:91], v[96:97] op_sel_hi:[1,0]
	v_pk_mul_f32 v[84:85], v[86:87], v[96:97] op_sel_hi:[1,0]
	v_pk_mul_f32 v[86:87], v[72:73], v[98:99]
	v_pk_mul_f32 v[98:99], v[80:81], v[96:97] op_sel_hi:[1,0]
	v_pk_mul_f32 v[80:81], v[82:83], v[96:97] op_sel_hi:[1,0]
	v_pk_mul_f32 v[94:95], v[78:79], v[94:95]
	v_pk_mul_f32 v[92:93], v[76:77], v[92:93]
	v_pk_mul_f32 v[90:91], v[70:71], v[90:91]
	v_pk_mul_f32 v[88:89], v[68:69], v[88:89]
	v_pk_mul_f32 v[84:85], v[74:75], v[84:85]
	v_pk_mul_f32 v[80:81], v[66:67], v[80:81]
	v_pk_mul_f32 v[82:83], v[64:65], v[98:99]
	s_and_b64 vcc, exec, s[4:5]
	s_cbranch_vccnz .LBB0_760
	s_add_i32 s21, s20, s39
	s_lshr_b32 s21, s21, 6
	v_mov_b32_e32 v96, s21
	v_cndmask_b32_e64 v96, v184, v96, s[44:45]
	v_lshlrev_b32_e32 v112, 7, v96
	v_add_u32_e32 v100, v185, v112
	ds_read_b128 v[96:99], v100
	ds_read_b128 v[100:103], v100 offset:16
	s_waitcnt lgkmcnt(1)
	v_mov_b32_e32 v106, v97
	v_mov_b32_e32 v107, v99
	v_pk_mul_f32 v[108:109], v[86:87], v[106:107]
	s_waitcnt lgkmcnt(0)
	v_mov_b32_e32 v110, v101
	v_mov_b32_e32 v111, v103
	v_mov_b32_e32 v101, v102
	v_mov_b32_e32 v97, v98
	v_pk_mul_f32 v[104:105], v[84:85], v[110:111]
	v_pk_fma_f32 v[102:103], v[92:93], v[96:97], v[108:109] neg_lo:[0,0,1] neg_hi:[0,0,1]
	v_pk_mul_f32 v[86:87], v[86:87], v[96:97]
	v_pk_mul_f32 v[84:85], v[84:85], v[100:101]
	v_add_u32_e32 v96, v186, v112
	v_pk_fma_f32 v[104:105], v[94:95], v[100:101], v[104:105] neg_lo:[0,0,1] neg_hi:[0,0,1]
	v_pk_fma_f32 v[84:85], v[94:95], v[110:111], v[84:85]
	v_pk_fma_f32 v[86:87], v[92:93], v[106:107], v[86:87]
	ds_read_b128 v[92:95], v96
	ds_read_b128 v[96:99], v96 offset:16
	s_waitcnt lgkmcnt(1)
	v_mov_b32_e32 v106, v93
	v_mov_b32_e32 v107, v95
	v_pk_mul_f32 v[108:109], v[82:83], v[106:107]
	s_waitcnt lgkmcnt(0)
	v_mov_b32_e32 v110, v97
	v_mov_b32_e32 v111, v99
	v_mov_b32_e32 v97, v98
	v_mov_b32_e32 v93, v94
	v_pk_mul_f32 v[100:101], v[80:81], v[110:111]
	v_pk_fma_f32 v[98:99], v[88:89], v[92:93], v[108:109] neg_lo:[0,0,1] neg_hi:[0,0,1]
	v_pk_mul_f32 v[82:83], v[82:83], v[92:93]
	v_pk_mul_f32 v[80:81], v[80:81], v[96:97]
	v_pk_fma_f32 v[100:101], v[90:91], v[96:97], v[100:101] neg_lo:[0,0,1] neg_hi:[0,0,1]
	v_pk_fma_f32 v[80:81], v[90:91], v[110:111], v[80:81]
	v_pk_fma_f32 v[82:83], v[88:89], v[106:107], v[82:83]
	v_mov_b64_e32 v[88:89], v[98:99]
	v_mov_b64_e32 v[92:93], v[102:103]
	v_mov_b64_e32 v[90:91], v[100:101]
	v_mov_b64_e32 v[94:95], v[104:105]
; #define LAS __attribute__((address_space(3)))
; DI float shx(float v, int m, int lane) { return __builtin_bit_cast(float, __builtin_amdgcn_ds_bpermute((lane ^ m) << 2, __builtin_bit_cast(int, v))); }
;     DI void operator()(const Acc& acc, const Unit& u, int wr, int wc, int fr, int fq) const {
;     ...
;                     const int rl = ai * HALF + wr * 64 + m * 16 + fr, r = rowb + rl;
;                     float ss = 0.f;
; #pragma unroll
;                     for (int bj = 0; bj < 2; ++bj)
; #pragma unroll
;                         for (int n = 0; n < 2; ++n) { const f32x4 a = acc[ai][bj][m][n]; ss += a[0] * a[0] + a[1] * a[1] + a[2] * a[2] + a[3] * a[3]; }
;                     ss += shx(ss, 16, 16 * fq + fr); ss += shx(ss, 32, 16 * fq + fr);
;                     const float rstd = rsqrtf(ss * (1.f / 64.f) + LN_EPS);
;                     f32x4 v[2][2];
; #pragma unroll
;                     for (int bj = 0; bj < 2; ++bj)
; #pragma unroll
;                         for (int n = 0; n < 2; ++n) v[bj][n] = acc[ai][bj][m][n] * rstd * g[bj][n];
;                     if (latent) {
;                         const int s = s0 + rl, pos = (fq >> 1) ? (s & 63) : (s >> 6);
; #pragma unroll
;                         for (int n = 0; n < 2; ++n) {
;                             const LAS float* tp = tab + (pos * 16 + 8 * (fq & 1) + 4 * n) * 2;
;                             const f32x4 t0 = *(const LAS f32x4*)tp, t1 = *(const LAS f32x4*)(tp + 4);
;                             const f32x4 cs = {t0[0], t0[2], t1[0], t1[2]}, sn = {t0[1], t0[3], t1[1], t1[3]};
;                             const f32x4 x1 = v[0][n], x2 = v[1][n];
;                             v[0][n] = x1 * cs - x2 * sn; v[1][n] = x2 * cs + x1 * sn;
;                         }
;                     }
; #pragma unroll
;                     for (int bj = 0; bj < 2; ++bj) {
;                         u32x4 o; o[0] = pk_bf16(v[bj][0][0], v[bj][0][1]); o[1] = pk_bf16(v[bj][0][2], v[bj][0][3]); o[2] = pk_bf16(v[bj][1][0], v[bj][1][1]); o[3] = pk_bf16(v[bj][1][2], v[bj][1][3]);
;                         bf16_t* dst = tile < 4 ? Q + (size_t)r * 1024 + (tile * 4 + wc) * 64 + dbase + 16 * bj
;                                                : Kd + ((size_t)(b * 4 + wc) * NKEY + kp0 + rl) * 64 + dbase + 16 * bj;
;                         *(u32x4*)dst = o;
;                     }
.LBB0_760:
	v_add_u32_e32 v96, s19, v156
	v_ashrrev_i32_e32 v97, 31, v96
	v_readlane_b32 s22, v254, 27
	v_lshlrev_b64 v[96:97], 11, v[96:97]
	v_lshl_add_u64 v[98:99], s[60:61], 0, v[156:157]
	v_readlane_b32 s23, v254, 28
	v_lshlrev_b64 v[98:99], 7, v[98:99]
	v_cvt_pk_bf16_f32 v92, v92, v93
	v_cvt_pk_bf16_f32 v93, v94, v95
	v_cvt_pk_bf16_f32 v94, v88, v89
	v_lshl_add_u64 v[88:89], s[22:23], 0, v[96:97]
	v_cvt_pk_bf16_f32 v95, v90, v91
	v_lshl_add_u64 v[88:89], s[58:59], 1, v[88:89]
	v_lshl_add_u64 v[90:91], s[26:27], 0, v[98:99]
	v_cndmask_b32_e64 v89, v89, v91, s[2:3]
	v_cndmask_b32_e64 v88, v88, v90, s[2:3]
	v_lshl_add_u64 v[90:91], v[88:89], 0, v[168:169]
	v_cvt_pk_bf16_f32 v88, v82, v83
	v_mov_b32_e32 v82, v57
	v_mov_b32_e32 v83, v61
	v_cvt_pk_bf16_f32 v89, v80, v81
	v_mov_b32_e32 v80, v56
	v_mov_b32_e32 v81, v60
	v_pk_mul_f32 v[82:83], v[82:83], v[82:83]
	v_cvt_pk_bf16_f32 v86, v86, v87
	v_pk_fma_f32 v[80:81], v[80:81], v[80:81], v[82:83]
	v_mov_b32_e32 v82, v58
	v_mov_b32_e32 v83, v62
	v_cvt_pk_bf16_f32 v87, v84, v85
	v_pk_fma_f32 v[80:81], v[82:83], v[82:83], v[80:81]
	v_mov_b32_e32 v82, v59
	v_mov_b32_e32 v83, v63
	v_mov_b32_e32 v84, v49
	v_mov_b32_e32 v85, v53
	v_pk_fma_f32 v[80:81], v[82:83], v[82:83], v[80:81]
	v_mov_b32_e32 v82, v48
	v_mov_b32_e32 v83, v52
	v_pk_mul_f32 v[84:85], v[84:85], v[84:85]
	v_add_f32_e32 v80, v80, v81
	v_pk_fma_f32 v[82:83], v[82:83], v[82:83], v[84:85]
	v_mov_b32_e32 v84, v50
	v_mov_b32_e32 v85, v54
	v_pk_fma_f32 v[82:83], v[84:85], v[84:85], v[82:83]
	v_mov_b32_e32 v84, v51
	v_mov_b32_e32 v85, v55
	v_pk_fma_f32 v[82:83], v[84:85], v[84:85], v[82:83]
	s_mov_b32 s21, 0x800000
	v_add_f32_e32 v80, v83, v80
	v_add_f32_e32 v80, v82, v80
	ds_bpermute_b32 v81, v180, v80
	s_nop 1
	v_mov_b32_dpp v202, v90 row_ror:8 row_mask:0xf bank_mask:0xf
	v_mov_b32_dpp v203, v91 row_ror:8 row_mask:0xf bank_mask:0xf
	v_mov_b32_e32 v210, 32
	v_mov_b32_e32 v211, 0
	v_mov_b32_e32 v206, v90
	v_mov_b32_e32 v207, v91
	v_lshl_add_u64 v[208:209], v[90:91], 0, v[210:211]
	v_lshl_add_u64 v[204:205], v[202:203], 0, v[210:211]
	v_mov_b32_dpp v212, v92 row_ror:8 row_mask:0xf bank_mask:0x3
	v_mov_b32_dpp v213, v93 row_ror:8 row_mask:0xf bank_mask:0x3
	v_mov_b32_dpp v214, v94 row_ror:8 row_mask:0xf bank_mask:0x3
	v_mov_b32_dpp v215, v95 row_ror:8 row_mask:0xf bank_mask:0x3
	v_mov_b32_dpp v206, v204 quad_perm:[0,1,2,3] row_mask:0xf bank_mask:0xc
	v_mov_b32_dpp v207, v205 quad_perm:[0,1,2,3] row_mask:0xf bank_mask:0xc
	v_mov_b32_dpp v208, v202 quad_perm:[0,1,2,3] row_mask:0xf bank_mask:0x3
	v_mov_b32_dpp v209, v203 quad_perm:[0,1,2,3] row_mask:0xf bank_mask:0x3
	v_mov_b32_dpp v92, v86 row_ror:8 row_mask:0xf bank_mask:0xc
	v_mov_b32_dpp v93, v87 row_ror:8 row_mask:0xf bank_mask:0xc
	v_mov_b32_dpp v94, v88 row_ror:8 row_mask:0xf bank_mask:0xc
	v_mov_b32_dpp v95, v89 row_ror:8 row_mask:0xf bank_mask:0xc
	v_mov_b32_dpp v86, v212 quad_perm:[0,1,2,3] row_mask:0xf bank_mask:0x3
	v_mov_b32_dpp v87, v213 quad_perm:[0,1,2,3] row_mask:0xf bank_mask:0x3
	v_mov_b32_dpp v88, v214 quad_perm:[0,1,2,3] row_mask:0xf bank_mask:0x3
	v_mov_b32_dpp v89, v215 quad_perm:[0,1,2,3] row_mask:0xf bank_mask:0x3
	global_store_dwordx4 v[206:207], v[92:95], off
	global_store_dwordx4 v[208:209], v[86:89], off
	s_nop 1
	s_waitcnt lgkmcnt(0)
	v_add_f32_e32 v80, v80, v81
	ds_bpermute_b32 v81, v181, v80
	s_waitcnt lgkmcnt(0)
	v_add_f32_e32 v80, v80, v81
	v_fmamk_f32 v80, v80, 0x3c800000, v250
	v_cmp_gt_f32_e32 vcc, s21, v80
	v_mul_f32_e32 v81, 0x4b800000, v80
	s_nop 0
	v_cndmask_b32_e32 v80, v80, v81, vcc
	v_rsq_f32_e32 v80, v80
	s_nop 0
	v_mul_f32_e32 v81, 0x45800000, v80
	v_cndmask_b32_e32 v80, v80, v81, vcc
	v_pk_mul_f32 v[82:83], v[52:53], v[80:81] op_sel_hi:[1,0]
	v_pk_mul_f32 v[60:61], v[60:61], v[80:81] op_sel_hi:[1,0]
	v_pk_mul_f32 v[62:63], v[62:63], v[80:81] op_sel_hi:[1,0]
	v_pk_mul_f32 v[56:57], v[56:57], v[80:81] op_sel_hi:[1,0]
	v_pk_mul_f32 v[58:59], v[58:59], v[80:81] op_sel_hi:[1,0]
	v_pk_mul_f32 v[52:53], v[54:55], v[80:81] op_sel_hi:[1,0]
	v_pk_mul_f32 v[54:55], v[72:73], v[82:83]
	v_pk_mul_f32 v[82:83], v[48:49], v[80:81] op_sel_hi:[1,0]
	v_pk_mul_f32 v[48:49], v[50:51], v[80:81] op_sel_hi:[1,0]
	v_pk_mul_f32 v[62:63], v[78:79], v[62:63]
	v_pk_mul_f32 v[60:61], v[76:77], v[60:61]
	v_pk_mul_f32 v[58:59], v[70:71], v[58:59]
	v_pk_mul_f32 v[56:57], v[68:69], v[56:57]
	v_pk_mul_f32 v[52:53], v[74:75], v[52:53]
	v_pk_mul_f32 v[48:49], v[66:67], v[48:49]
	v_pk_mul_f32 v[50:51], v[64:65], v[82:83]
	s_and_b64 vcc, exec, s[4:5]
	s_cbranch_vccnz .LBB0_762
	v_add_u32_e32 v80, s20, v158
	v_lshrrev_b32_e32 v80, 6, v80
	v_cndmask_b32_e64 v80, v151, v80, s[44:45]
	v_lshlrev_b32_e32 v96, 7, v80
	v_add_u32_e32 v84, v185, v96
	ds_read_b128 v[80:83], v84
	ds_read_b128 v[84:87], v84 offset:16
	s_waitcnt lgkmcnt(1)
	v_mov_b32_e32 v90, v81
	v_mov_b32_e32 v91, v83
	v_pk_mul_f32 v[92:93], v[54:55], v[90:91]
	s_waitcnt lgkmcnt(0)
	v_mov_b32_e32 v94, v85
	v_mov_b32_e32 v95, v87
	v_mov_b32_e32 v85, v86
	v_mov_b32_e32 v81, v82
	v_pk_mul_f32 v[88:89], v[52:53], v[94:95]
	v_pk_fma_f32 v[86:87], v[60:61], v[80:81], v[92:93] neg_lo:[0,0,1] neg_hi:[0,0,1]
	v_pk_mul_f32 v[54:55], v[54:55], v[80:81]
	v_pk_mul_f32 v[52:53], v[52:53], v[84:85]
	v_add_u32_e32 v80, v186, v96
	v_pk_fma_f32 v[88:89], v[62:63], v[84:85], v[88:89] neg_lo:[0,0,1] neg_hi:[0,0,1]
	v_pk_fma_f32 v[52:53], v[62:63], v[94:95], v[52:53]
	v_pk_fma_f32 v[54:55], v[60:61], v[90:91], v[54:55]
	ds_read_b128 v[60:63], v80
	ds_read_b128 v[80:83], v80 offset:16
	s_waitcnt lgkmcnt(1)
	v_mov_b32_e32 v90, v61
	v_mov_b32_e32 v91, v63
	v_pk_mul_f32 v[92:93], v[50:51], v[90:91]
	s_waitcnt lgkmcnt(0)
	v_mov_b32_e32 v94, v81
	v_mov_b32_e32 v95, v83
	v_mov_b32_e32 v81, v82
	v_mov_b32_e32 v61, v62
	v_pk_mul_f32 v[84:85], v[48:49], v[94:95]
	v_pk_fma_f32 v[82:83], v[56:57], v[60:61], v[92:93] neg_lo:[0,0,1] neg_hi:[0,0,1]
	v_pk_mul_f32 v[50:51], v[50:51], v[60:61]
	v_pk_mul_f32 v[48:49], v[48:49], v[80:81]
	v_pk_fma_f32 v[84:85], v[58:59], v[80:81], v[84:85] neg_lo:[0,0,1] neg_hi:[0,0,1]
	v_pk_fma_f32 v[48:49], v[58:59], v[94:95], v[48:49]
	v_pk_fma_f32 v[50:51], v[56:57], v[90:91], v[50:51]
	v_mov_b64_e32 v[56:57], v[82:83]
	v_mov_b64_e32 v[60:61], v[86:87]
	v_mov_b64_e32 v[58:59], v[84:85]
	v_mov_b64_e32 v[62:63], v[88:89]
; #define LAS __attribute__((address_space(3)))
; DI float shx(float v, int m, int lane) { return __builtin_bit_cast(float, __builtin_amdgcn_ds_bpermute((lane ^ m) << 2, __builtin_bit_cast(int, v))); }
;     DI void operator()(const Acc& acc, const Unit& u, int wr, int wc, int fr, int fq) const {
;     ...
;                     const int rl = ai * HALF + wr * 64 + m * 16 + fr, r = rowb + rl;
;                     float ss = 0.f;
; #pragma unroll
;                     for (int bj = 0; bj < 2; ++bj)
; #pragma unroll
;                         for (int n = 0; n < 2; ++n) { const f32x4 a = acc[ai][bj][m][n]; ss += a[0] * a[0] + a[1] * a[1] + a[2] * a[2] + a[3] * a[3]; }
;                     ss += shx(ss, 16, 16 * fq + fr); ss += shx(ss, 32, 16 * fq + fr);
;                     const float rstd = rsqrtf(ss * (1.f / 64.f) + LN_EPS);
;                     f32x4 v[2][2];
; #pragma unroll
;                     for (int bj = 0; bj < 2; ++bj)
; #pragma unroll
;                         for (int n = 0; n < 2; ++n) v[bj][n] = acc[ai][bj][m][n] * rstd * g[bj][n];
;                     if (latent) {
;                         const int s = s0 + rl, pos = (fq >> 1) ? (s & 63) : (s >> 6);
; #pragma unroll
;                         for (int n = 0; n < 2; ++n) {
;                             const LAS float* tp = tab + (pos * 16 + 8 * (fq & 1) + 4 * n) * 2;
;                             const f32x4 t0 = *(const LAS f32x4*)tp, t1 = *(const LAS f32x4*)(tp + 4);
;                             const f32x4 cs = {t0[0], t0[2], t1[0], t1[2]}, sn = {t0[1], t0[3], t1[1], t1[3]};
;                             const f32x4 x1 = v[0][n], x2 = v[1][n];
;                             v[0][n] = x1 * cs - x2 * sn; v[1][n] = x2 * cs + x1 * sn;
;                         }
;                     }
; #pragma unroll
;                     for (int bj = 0; bj < 2; ++bj) {
;                         u32x4 o; o[0] = pk_bf16(v[bj][0][0], v[bj][0][1]); o[1] = pk_bf16(v[bj][0][2], v[bj][0][3]); o[2] = pk_bf16(v[bj][1][0], v[bj][1][1]); o[3] = pk_bf16(v[bj][1][2], v[bj][1][3]);
;                         bf16_t* dst = tile < 4 ? Q + (size_t)r * 1024 + (tile * 4 + wc) * 64 + dbase + 16 * bj
;                                                : Kd + ((size_t)(b * 4 + wc) * NKEY + kp0 + rl) * 64 + dbase + 16 * bj;
;                         *(u32x4*)dst = o;
;                     }
.LBB0_762:
	v_add_u32_e32 v80, s19, v158
	v_ashrrev_i32_e32 v81, 31, v80
	v_readlane_b32 s22, v254, 27
	v_lshlrev_b64 v[80:81], 11, v[80:81]
	v_lshl_add_u64 v[82:83], s[60:61], 0, v[158:159]
	v_readlane_b32 s23, v254, 28
	v_lshlrev_b64 v[82:83], 7, v[82:83]
	v_cvt_pk_bf16_f32 v60, v60, v61
	v_cvt_pk_bf16_f32 v61, v62, v63
	v_cvt_pk_bf16_f32 v62, v56, v57
	v_lshl_add_u64 v[56:57], s[22:23], 0, v[80:81]
	v_cvt_pk_bf16_f32 v63, v58, v59
	v_lshl_add_u64 v[56:57], s[58:59], 1, v[56:57]
	v_lshl_add_u64 v[58:59], s[26:27], 0, v[82:83]
	v_cndmask_b32_e64 v57, v57, v59, s[2:3]
	v_cndmask_b32_e64 v56, v56, v58, s[2:3]
	v_lshl_add_u64 v[58:59], v[56:57], 0, v[168:169]
	v_cvt_pk_bf16_f32 v56, v50, v51
	v_mov_b32_e32 v50, v41
	v_mov_b32_e32 v51, v45
	v_cvt_pk_bf16_f32 v57, v48, v49
	v_mov_b32_e32 v48, v40
	v_mov_b32_e32 v49, v44
	v_pk_mul_f32 v[50:51], v[50:51], v[50:51]
	v_cvt_pk_bf16_f32 v54, v54, v55
	v_pk_fma_f32 v[48:49], v[48:49], v[48:49], v[50:51]
	v_mov_b32_e32 v50, v42
	v_mov_b32_e32 v51, v46
	v_cvt_pk_bf16_f32 v55, v52, v53
	v_pk_fma_f32 v[48:49], v[50:51], v[50:51], v[48:49]
	v_mov_b32_e32 v50, v43
	v_mov_b32_e32 v51, v47
	v_mov_b32_e32 v52, v33
	v_mov_b32_e32 v53, v37
	v_pk_fma_f32 v[48:49], v[50:51], v[50:51], v[48:49]
	v_mov_b32_e32 v50, v32
	v_mov_b32_e32 v51, v36
	v_pk_mul_f32 v[52:53], v[52:53], v[52:53]
	v_add_f32_e32 v48, v48, v49
	v_pk_fma_f32 v[50:51], v[50:51], v[50:51], v[52:53]
	v_mov_b32_e32 v52, v34
	v_mov_b32_e32 v53, v38
	v_pk_fma_f32 v[50:51], v[52:53], v[52:53], v[50:51]
	v_mov_b32_e32 v52, v35
	v_mov_b32_e32 v53, v39
	v_pk_fma_f32 v[50:51], v[52:53], v[52:53], v[50:51]
	v_add_f32_e32 v48, v51, v48
	v_add_f32_e32 v48, v50, v48
	ds_bpermute_b32 v49, v180, v48
	s_nop 1
	v_mov_b32_dpp v202, v58 row_ror:8 row_mask:0xf bank_mask:0xf
	v_mov_b32_dpp v203, v59 row_ror:8 row_mask:0xf bank_mask:0xf
	v_mov_b32_e32 v210, 32
	v_mov_b32_e32 v211, 0
	v_mov_b32_e32 v206, v58
	v_mov_b32_e32 v207, v59
	v_lshl_add_u64 v[208:209], v[58:59], 0, v[210:211]
	v_lshl_add_u64 v[204:205], v[202:203], 0, v[210:211]
	v_mov_b32_dpp v212, v60 row_ror:8 row_mask:0xf bank_mask:0x3
	v_mov_b32_dpp v213, v61 row_ror:8 row_mask:0xf bank_mask:0x3
	v_mov_b32_dpp v214, v62 row_ror:8 row_mask:0xf bank_mask:0x3
	v_mov_b32_dpp v215, v63 row_ror:8 row_mask:0xf bank_mask:0x3
	v_mov_b32_dpp v206, v204 quad_perm:[0,1,2,3] row_mask:0xf bank_mask:0xc
	v_mov_b32_dpp v207, v205 quad_perm:[0,1,2,3] row_mask:0xf bank_mask:0xc
	v_mov_b32_dpp v208, v202 quad_perm:[0,1,2,3] row_mask:0xf bank_mask:0x3
	v_mov_b32_dpp v209, v203 quad_perm:[0,1,2,3] row_mask:0xf bank_mask:0x3
	v_mov_b32_dpp v60, v54 row_ror:8 row_mask:0xf bank_mask:0xc
	v_mov_b32_dpp v61, v55 row_ror:8 row_mask:0xf bank_mask:0xc
	v_mov_b32_dpp v62, v56 row_ror:8 row_mask:0xf bank_mask:0xc
	v_mov_b32_dpp v63, v57 row_ror:8 row_mask:0xf bank_mask:0xc
	v_mov_b32_dpp v54, v212 quad_perm:[0,1,2,3] row_mask:0xf bank_mask:0x3
	v_mov_b32_dpp v55, v213 quad_perm:[0,1,2,3] row_mask:0xf bank_mask:0x3
	v_mov_b32_dpp v56, v214 quad_perm:[0,1,2,3] row_mask:0xf bank_mask:0x3
	v_mov_b32_dpp v57, v215 quad_perm:[0,1,2,3] row_mask:0xf bank_mask:0x3
	global_store_dwordx4 v[206:207], v[60:63], off
	global_store_dwordx4 v[208:209], v[54:57], off
	s_nop 1
	s_waitcnt lgkmcnt(0)
	v_add_f32_e32 v48, v48, v49
	ds_bpermute_b32 v49, v181, v48
	s_waitcnt lgkmcnt(0)
	v_add_f32_e32 v48, v48, v49
	v_fmamk_f32 v48, v48, 0x3c800000, v250
	v_cmp_gt_f32_e32 vcc, s21, v48
	v_mul_f32_e32 v49, 0x4b800000, v48
	s_nop 0
	v_cndmask_b32_e32 v48, v48, v49, vcc
	v_rsq_f32_e32 v48, v48
	s_nop 0
	v_mul_f32_e32 v49, 0x45800000, v48
	v_cndmask_b32_e32 v48, v48, v49, vcc
	v_pk_mul_f32 v[50:51], v[36:37], v[48:49] op_sel_hi:[1,0]
	v_pk_mul_f32 v[44:45], v[44:45], v[48:49] op_sel_hi:[1,0]
	v_pk_mul_f32 v[46:47], v[46:47], v[48:49] op_sel_hi:[1,0]
	v_pk_mul_f32 v[40:41], v[40:41], v[48:49] op_sel_hi:[1,0]
	v_pk_mul_f32 v[42:43], v[42:43], v[48:49] op_sel_hi:[1,0]
	v_pk_mul_f32 v[36:37], v[38:39], v[48:49] op_sel_hi:[1,0]
	v_pk_mul_f32 v[38:39], v[72:73], v[50:51]
	v_pk_mul_f32 v[50:51], v[32:33], v[48:49] op_sel_hi:[1,0]
	v_pk_mul_f32 v[32:33], v[34:35], v[48:49] op_sel_hi:[1,0]
	v_pk_mul_f32 v[46:47], v[78:79], v[46:47]
	v_pk_mul_f32 v[44:45], v[76:77], v[44:45]
	v_pk_mul_f32 v[42:43], v[70:71], v[42:43]
	v_pk_mul_f32 v[40:41], v[68:69], v[40:41]
	v_pk_mul_f32 v[36:37], v[74:75], v[36:37]
	v_pk_mul_f32 v[32:33], v[66:67], v[32:33]
	v_pk_mul_f32 v[34:35], v[64:65], v[50:51]
	s_and_b64 vcc, exec, s[4:5]
	s_cbranch_vccnz .LBB0_764
	v_add_u32_e32 v48, s20, v160
	v_lshrrev_b32_e32 v48, 6, v48
	v_cndmask_b32_e64 v48, v182, v48, s[44:45]
	v_lshlrev_b32_e32 v80, 7, v48
	v_add_u32_e32 v52, v185, v80
	ds_read_b128 v[48:51], v52
	ds_read_b128 v[52:55], v52 offset:16
	s_waitcnt lgkmcnt(1)
	v_mov_b32_e32 v58, v49
	v_mov_b32_e32 v59, v51
	v_pk_mul_f32 v[60:61], v[38:39], v[58:59]
	s_waitcnt lgkmcnt(0)
	v_mov_b32_e32 v62, v53
	v_mov_b32_e32 v63, v55
	v_mov_b32_e32 v53, v54
	v_mov_b32_e32 v49, v50
	v_pk_mul_f32 v[56:57], v[36:37], v[62:63]
	v_pk_fma_f32 v[54:55], v[44:45], v[48:49], v[60:61] neg_lo:[0,0,1] neg_hi:[0,0,1]
	v_pk_mul_f32 v[38:39], v[38:39], v[48:49]
	v_pk_mul_f32 v[36:37], v[36:37], v[52:53]
	v_add_u32_e32 v48, v186, v80
	v_pk_fma_f32 v[56:57], v[46:47], v[52:53], v[56:57] neg_lo:[0,0,1] neg_hi:[0,0,1]
	v_pk_fma_f32 v[36:37], v[46:47], v[62:63], v[36:37]
	v_pk_fma_f32 v[38:39], v[44:45], v[58:59], v[38:39]
	ds_read_b128 v[44:47], v48
	ds_read_b128 v[48:51], v48 offset:16
	s_waitcnt lgkmcnt(1)
	v_mov_b32_e32 v58, v45
	v_mov_b32_e32 v59, v47
	v_pk_mul_f32 v[60:61], v[34:35], v[58:59]
	s_waitcnt lgkmcnt(0)
	v_mov_b32_e32 v62, v49
	v_mov_b32_e32 v63, v51
	v_mov_b32_e32 v49, v50
	v_mov_b32_e32 v45, v46
	v_pk_mul_f32 v[52:53], v[32:33], v[62:63]
	v_pk_fma_f32 v[50:51], v[40:41], v[44:45], v[60:61] neg_lo:[0,0,1] neg_hi:[0,0,1]
	v_pk_mul_f32 v[34:35], v[34:35], v[44:45]
	v_pk_mul_f32 v[32:33], v[32:33], v[48:49]
	v_pk_fma_f32 v[52:53], v[42:43], v[48:49], v[52:53] neg_lo:[0,0,1] neg_hi:[0,0,1]
	v_pk_fma_f32 v[32:33], v[42:43], v[62:63], v[32:33]
	v_pk_fma_f32 v[34:35], v[40:41], v[58:59], v[34:35]
	v_mov_b64_e32 v[40:41], v[50:51]
	v_mov_b64_e32 v[44:45], v[54:55]
	v_mov_b64_e32 v[42:43], v[52:53]
	v_mov_b64_e32 v[46:47], v[56:57]
; #define LAS __attribute__((address_space(3)))
; DI float shx(float v, int m, int lane) { return __builtin_bit_cast(float, __builtin_amdgcn_ds_bpermute((lane ^ m) << 2, __builtin_bit_cast(int, v))); }
;     DI void operator()(const Acc& acc, const Unit& u, int wr, int wc, int fr, int fq) const {
;     ...
;                     const int rl = ai * HALF + wr * 64 + m * 16 + fr, r = rowb + rl;
;                     float ss = 0.f;
; #pragma unroll
;                     for (int bj = 0; bj < 2; ++bj)
; #pragma unroll
;                         for (int n = 0; n < 2; ++n) { const f32x4 a = acc[ai][bj][m][n]; ss += a[0] * a[0] + a[1] * a[1] + a[2] * a[2] + a[3] * a[3]; }
;                     ss += shx(ss, 16, 16 * fq + fr); ss += shx(ss, 32, 16 * fq + fr);
;                     const float rstd = rsqrtf(ss * (1.f / 64.f) + LN_EPS);
;                     f32x4 v[2][2];
; #pragma unroll
;                     for (int bj = 0; bj < 2; ++bj)
; #pragma unroll
;                         for (int n = 0; n < 2; ++n) v[bj][n] = acc[ai][bj][m][n] * rstd * g[bj][n];
;                     if (latent) {
;                         const int s = s0 + rl, pos = (fq >> 1) ? (s & 63) : (s >> 6);
; #pragma unroll
;                         for (int n = 0; n < 2; ++n) {
;                             const LAS float* tp = tab + (pos * 16 + 8 * (fq & 1) + 4 * n) * 2;
;                             const f32x4 t0 = *(const LAS f32x4*)tp, t1 = *(const LAS f32x4*)(tp + 4);
;                             const f32x4 cs = {t0[0], t0[2], t1[0], t1[2]}, sn = {t0[1], t0[3], t1[1], t1[3]};
;                             const f32x4 x1 = v[0][n], x2 = v[1][n];
;                             v[0][n] = x1 * cs - x2 * sn; v[1][n] = x2 * cs + x1 * sn;
;                         }
;                     }
; #pragma unroll
;                     for (int bj = 0; bj < 2; ++bj) {
;                         u32x4 o; o[0] = pk_bf16(v[bj][0][0], v[bj][0][1]); o[1] = pk_bf16(v[bj][0][2], v[bj][0][3]); o[2] = pk_bf16(v[bj][1][0], v[bj][1][1]); o[3] = pk_bf16(v[bj][1][2], v[bj][1][3]);
;                         bf16_t* dst = tile < 4 ? Q + (size_t)r * 1024 + (tile * 4 + wc) * 64 + dbase + 16 * bj
;                                                : Kd + ((size_t)(b * 4 + wc) * NKEY + kp0 + rl) * 64 + dbase + 16 * bj;
;                         *(u32x4*)dst = o;
;                     }
.LBB0_764:
	v_add_u32_e32 v48, s19, v160
	v_ashrrev_i32_e32 v49, 31, v48
	v_readlane_b32 s22, v254, 27
	v_lshlrev_b64 v[48:49], 11, v[48:49]
	v_lshl_add_u64 v[50:51], s[60:61], 0, v[160:161]
	v_readlane_b32 s23, v254, 28
	v_lshlrev_b64 v[50:51], 7, v[50:51]
	v_cvt_pk_bf16_f32 v44, v44, v45
	v_cvt_pk_bf16_f32 v45, v46, v47
	v_cvt_pk_bf16_f32 v46, v40, v41
	v_lshl_add_u64 v[40:41], s[22:23], 0, v[48:49]
	v_cvt_pk_bf16_f32 v47, v42, v43
	v_lshl_add_u64 v[40:41], s[58:59], 1, v[40:41]
	v_lshl_add_u64 v[42:43], s[26:27], 0, v[50:51]
	v_cndmask_b32_e64 v41, v41, v43, s[2:3]
	v_cndmask_b32_e64 v40, v40, v42, s[2:3]
	v_lshl_add_u64 v[42:43], v[40:41], 0, v[168:169]
	v_cvt_pk_bf16_f32 v40, v34, v35
	v_mov_b32_e32 v34, v25
	v_mov_b32_e32 v35, v29
	v_cvt_pk_bf16_f32 v41, v32, v33
	v_mov_b32_e32 v32, v24
	v_mov_b32_e32 v33, v28
	v_pk_mul_f32 v[34:35], v[34:35], v[34:35]
	v_cvt_pk_bf16_f32 v38, v38, v39
	v_pk_fma_f32 v[32:33], v[32:33], v[32:33], v[34:35]
	v_mov_b32_e32 v34, v26
	v_mov_b32_e32 v35, v30
	v_cvt_pk_bf16_f32 v39, v36, v37
	v_pk_fma_f32 v[32:33], v[34:35], v[34:35], v[32:33]
	v_mov_b32_e32 v34, v27
	v_mov_b32_e32 v35, v31
	v_mov_b32_e32 v36, v17
	v_mov_b32_e32 v37, v21
	v_pk_fma_f32 v[32:33], v[34:35], v[34:35], v[32:33]
	v_mov_b32_e32 v34, v16
	v_mov_b32_e32 v35, v20
	v_pk_mul_f32 v[36:37], v[36:37], v[36:37]
	v_add_f32_e32 v32, v32, v33
	v_pk_fma_f32 v[34:35], v[34:35], v[34:35], v[36:37]
	v_mov_b32_e32 v36, v18
	v_mov_b32_e32 v37, v22
	v_pk_fma_f32 v[34:35], v[36:37], v[36:37], v[34:35]
	v_mov_b32_e32 v36, v19
	v_mov_b32_e32 v37, v23
	v_pk_fma_f32 v[34:35], v[36:37], v[36:37], v[34:35]
	v_add_f32_e32 v32, v35, v32
	v_add_f32_e32 v32, v34, v32
	ds_bpermute_b32 v33, v180, v32
	s_nop 1
	v_mov_b32_dpp v202, v42 row_ror:8 row_mask:0xf bank_mask:0xf
	v_mov_b32_dpp v203, v43 row_ror:8 row_mask:0xf bank_mask:0xf
	v_mov_b32_e32 v210, 32
	v_mov_b32_e32 v211, 0
	v_mov_b32_e32 v206, v42
	v_mov_b32_e32 v207, v43
	v_lshl_add_u64 v[208:209], v[42:43], 0, v[210:211]
	v_lshl_add_u64 v[204:205], v[202:203], 0, v[210:211]
	v_mov_b32_dpp v212, v44 row_ror:8 row_mask:0xf bank_mask:0x3
	v_mov_b32_dpp v213, v45 row_ror:8 row_mask:0xf bank_mask:0x3
	v_mov_b32_dpp v214, v46 row_ror:8 row_mask:0xf bank_mask:0x3
	v_mov_b32_dpp v215, v47 row_ror:8 row_mask:0xf bank_mask:0x3
	v_mov_b32_dpp v206, v204 quad_perm:[0,1,2,3] row_mask:0xf bank_mask:0xc
	v_mov_b32_dpp v207, v205 quad_perm:[0,1,2,3] row_mask:0xf bank_mask:0xc
	v_mov_b32_dpp v208, v202 quad_perm:[0,1,2,3] row_mask:0xf bank_mask:0x3
	v_mov_b32_dpp v209, v203 quad_perm:[0,1,2,3] row_mask:0xf bank_mask:0x3
	v_mov_b32_dpp v44, v38 row_ror:8 row_mask:0xf bank_mask:0xc
	v_mov_b32_dpp v45, v39 row_ror:8 row_mask:0xf bank_mask:0xc
	v_mov_b32_dpp v46, v40 row_ror:8 row_mask:0xf bank_mask:0xc
	v_mov_b32_dpp v47, v41 row_ror:8 row_mask:0xf bank_mask:0xc
	v_mov_b32_dpp v38, v212 quad_perm:[0,1,2,3] row_mask:0xf bank_mask:0x3
	v_mov_b32_dpp v39, v213 quad_perm:[0,1,2,3] row_mask:0xf bank_mask:0x3
	v_mov_b32_dpp v40, v214 quad_perm:[0,1,2,3] row_mask:0xf bank_mask:0x3
	v_mov_b32_dpp v41, v215 quad_perm:[0,1,2,3] row_mask:0xf bank_mask:0x3
	global_store_dwordx4 v[206:207], v[44:47], off
	global_store_dwordx4 v[208:209], v[38:41], off
	s_nop 1
	s_waitcnt lgkmcnt(0)
	v_add_f32_e32 v32, v32, v33
	ds_bpermute_b32 v33, v181, v32
	s_waitcnt lgkmcnt(0)
	v_add_f32_e32 v32, v32, v33
	v_fmamk_f32 v32, v32, 0x3c800000, v250
	v_cmp_gt_f32_e32 vcc, s21, v32
	v_mul_f32_e32 v33, 0x4b800000, v32
	s_nop 0
	v_cndmask_b32_e32 v32, v32, v33, vcc
	v_rsq_f32_e32 v32, v32
	s_nop 0
	v_mul_f32_e32 v33, 0x45800000, v32
	v_cndmask_b32_e32 v32, v32, v33, vcc
	v_pk_mul_f32 v[34:35], v[20:21], v[32:33] op_sel_hi:[1,0]
	v_pk_mul_f32 v[28:29], v[28:29], v[32:33] op_sel_hi:[1,0]
	v_pk_mul_f32 v[30:31], v[30:31], v[32:33] op_sel_hi:[1,0]
	v_pk_mul_f32 v[24:25], v[24:25], v[32:33] op_sel_hi:[1,0]
	v_pk_mul_f32 v[26:27], v[26:27], v[32:33] op_sel_hi:[1,0]
	v_pk_mul_f32 v[20:21], v[22:23], v[32:33] op_sel_hi:[1,0]
	v_pk_mul_f32 v[22:23], v[72:73], v[34:35]
	v_pk_mul_f32 v[34:35], v[16:17], v[32:33] op_sel_hi:[1,0]
	v_pk_mul_f32 v[16:17], v[18:19], v[32:33] op_sel_hi:[1,0]
	v_pk_mul_f32 v[30:31], v[78:79], v[30:31]
	v_pk_mul_f32 v[28:29], v[76:77], v[28:29]
	v_pk_mul_f32 v[26:27], v[70:71], v[26:27]
	v_pk_mul_f32 v[24:25], v[68:69], v[24:25]
	v_pk_mul_f32 v[20:21], v[74:75], v[20:21]
	v_pk_mul_f32 v[16:17], v[66:67], v[16:17]
	v_pk_mul_f32 v[18:19], v[64:65], v[34:35]
	s_and_b64 vcc, exec, s[4:5]
	s_cbranch_vccnz .LBB0_766
	v_add_u32_e32 v32, s20, v162
	v_lshrrev_b32_e32 v32, 6, v32
	v_cndmask_b32_e64 v32, v183, v32, s[44:45]
	v_lshlrev_b32_e32 v48, 7, v32
	v_add_u32_e32 v36, v185, v48
	ds_read_b128 v[32:35], v36
	ds_read_b128 v[36:39], v36 offset:16
	s_waitcnt lgkmcnt(1)
	v_mov_b32_e32 v42, v33
	v_mov_b32_e32 v43, v35
	v_pk_mul_f32 v[44:45], v[22:23], v[42:43]
	s_waitcnt lgkmcnt(0)
	v_mov_b32_e32 v46, v37
	v_mov_b32_e32 v47, v39
	v_mov_b32_e32 v37, v38
	v_mov_b32_e32 v33, v34
	v_pk_mul_f32 v[40:41], v[20:21], v[46:47]
	v_pk_fma_f32 v[38:39], v[28:29], v[32:33], v[44:45] neg_lo:[0,0,1] neg_hi:[0,0,1]
	v_pk_mul_f32 v[22:23], v[22:23], v[32:33]
	v_pk_mul_f32 v[20:21], v[20:21], v[36:37]
	v_add_u32_e32 v32, v186, v48
	v_pk_fma_f32 v[40:41], v[30:31], v[36:37], v[40:41] neg_lo:[0,0,1] neg_hi:[0,0,1]
	v_pk_fma_f32 v[20:21], v[30:31], v[46:47], v[20:21]
	v_pk_fma_f32 v[22:23], v[28:29], v[42:43], v[22:23]
	ds_read_b128 v[28:31], v32
	ds_read_b128 v[32:35], v32 offset:16
	s_waitcnt lgkmcnt(1)
	v_mov_b32_e32 v42, v29
	v_mov_b32_e32 v43, v31
	v_pk_mul_f32 v[44:45], v[18:19], v[42:43]
	s_waitcnt lgkmcnt(0)
	v_mov_b32_e32 v46, v33
	v_mov_b32_e32 v47, v35
	v_mov_b32_e32 v33, v34
	v_mov_b32_e32 v29, v30
	v_pk_mul_f32 v[36:37], v[16:17], v[46:47]
	v_pk_fma_f32 v[34:35], v[24:25], v[28:29], v[44:45] neg_lo:[0,0,1] neg_hi:[0,0,1]
	v_pk_mul_f32 v[18:19], v[18:19], v[28:29]
	v_pk_mul_f32 v[16:17], v[16:17], v[32:33]
	v_pk_fma_f32 v[36:37], v[26:27], v[32:33], v[36:37] neg_lo:[0,0,1] neg_hi:[0,0,1]
	v_pk_fma_f32 v[16:17], v[26:27], v[46:47], v[16:17]
	v_pk_fma_f32 v[18:19], v[24:25], v[42:43], v[18:19]
	v_mov_b64_e32 v[24:25], v[34:35]
	v_mov_b64_e32 v[28:29], v[38:39]
	v_mov_b64_e32 v[26:27], v[36:37]
	v_mov_b64_e32 v[30:31], v[40:41]
; #define LAS __attribute__((address_space(3)))
; DI float shx(float v, int m, int lane) { return __builtin_bit_cast(float, __builtin_amdgcn_ds_bpermute((lane ^ m) << 2, __builtin_bit_cast(int, v))); }
;     DI void operator()(const Acc& acc, const Unit& u, int wr, int wc, int fr, int fq) const {
;     ...
;                     const int rl = ai * HALF + wr * 64 + m * 16 + fr, r = rowb + rl;
;                     float ss = 0.f;
; #pragma unroll
;                     for (int bj = 0; bj < 2; ++bj)
; #pragma unroll
;                         for (int n = 0; n < 2; ++n) { const f32x4 a = acc[ai][bj][m][n]; ss += a[0] * a[0] + a[1] * a[1] + a[2] * a[2] + a[3] * a[3]; }
;                     ss += shx(ss, 16, 16 * fq + fr); ss += shx(ss, 32, 16 * fq + fr);
;                     const float rstd = rsqrtf(ss * (1.f / 64.f) + LN_EPS);
;                     f32x4 v[2][2];
; #pragma unroll
;                     for (int bj = 0; bj < 2; ++bj)
; #pragma unroll
;                         for (int n = 0; n < 2; ++n) v[bj][n] = acc[ai][bj][m][n] * rstd * g[bj][n];
;                     if (latent) {
;                         const int s = s0 + rl, pos = (fq >> 1) ? (s & 63) : (s >> 6);
; #pragma unroll
;                         for (int n = 0; n < 2; ++n) {
;                             const LAS float* tp = tab + (pos * 16 + 8 * (fq & 1) + 4 * n) * 2;
;                             const f32x4 t0 = *(const LAS f32x4*)tp, t1 = *(const LAS f32x4*)(tp + 4);
;                             const f32x4 cs = {t0[0], t0[2], t1[0], t1[2]}, sn = {t0[1], t0[3], t1[1], t1[3]};
;                             const f32x4 x1 = v[0][n], x2 = v[1][n];
;                             v[0][n] = x1 * cs - x2 * sn; v[1][n] = x2 * cs + x1 * sn;
;                         }
;                     }
; #pragma unroll
;                     for (int bj = 0; bj < 2; ++bj) {
;                         u32x4 o; o[0] = pk_bf16(v[bj][0][0], v[bj][0][1]); o[1] = pk_bf16(v[bj][0][2], v[bj][0][3]); o[2] = pk_bf16(v[bj][1][0], v[bj][1][1]); o[3] = pk_bf16(v[bj][1][2], v[bj][1][3]);
;                         bf16_t* dst = tile < 4 ? Q + (size_t)r * 1024 + (tile * 4 + wc) * 64 + dbase + 16 * bj
;                                                : Kd + ((size_t)(b * 4 + wc) * NKEY + kp0 + rl) * 64 + dbase + 16 * bj;
;                         *(u32x4*)dst = o;
;                     }
.LBB0_766:
	v_add_u32_e32 v32, s19, v162
	v_ashrrev_i32_e32 v33, 31, v32
	v_readlane_b32 s22, v254, 27
	v_lshlrev_b64 v[32:33], 11, v[32:33]
	v_lshl_add_u64 v[34:35], s[60:61], 0, v[162:163]
	v_readlane_b32 s23, v254, 28
	v_lshlrev_b64 v[34:35], 7, v[34:35]
	v_cvt_pk_bf16_f32 v28, v28, v29
	v_cvt_pk_bf16_f32 v29, v30, v31
	v_cvt_pk_bf16_f32 v30, v24, v25
	v_lshl_add_u64 v[24:25], s[22:23], 0, v[32:33]
	v_cvt_pk_bf16_f32 v31, v26, v27
	v_lshl_add_u64 v[24:25], s[58:59], 1, v[24:25]
	v_lshl_add_u64 v[26:27], s[26:27], 0, v[34:35]
	v_cndmask_b32_e64 v25, v25, v27, s[2:3]
	v_cndmask_b32_e64 v24, v24, v26, s[2:3]
	v_lshl_add_u64 v[26:27], v[24:25], 0, v[168:169]
	v_cvt_pk_bf16_f32 v24, v18, v19
	v_mov_b32_e32 v18, v9
	v_mov_b32_e32 v19, v13
	v_cvt_pk_bf16_f32 v25, v16, v17
	v_mov_b32_e32 v16, v8
	v_mov_b32_e32 v17, v12
	v_pk_mul_f32 v[18:19], v[18:19], v[18:19]
	v_cvt_pk_bf16_f32 v22, v22, v23
	v_pk_fma_f32 v[16:17], v[16:17], v[16:17], v[18:19]
	v_mov_b32_e32 v18, v10
	v_mov_b32_e32 v19, v14
	v_cvt_pk_bf16_f32 v23, v20, v21
	v_pk_fma_f32 v[16:17], v[18:19], v[18:19], v[16:17]
	v_mov_b32_e32 v18, v11
	v_mov_b32_e32 v19, v15
	v_mov_b32_e32 v20, v5
	v_mov_b32_e32 v21, v1
	v_pk_fma_f32 v[16:17], v[18:19], v[18:19], v[16:17]
	v_mov_b32_e32 v18, v4
	v_mov_b32_e32 v19, v0
	v_pk_mul_f32 v[20:21], v[20:21], v[20:21]
	v_add_f32_e32 v16, v16, v17
	v_pk_fma_f32 v[18:19], v[18:19], v[18:19], v[20:21]
	v_mov_b32_e32 v20, v6
	v_mov_b32_e32 v21, v2
	v_pk_fma_f32 v[18:19], v[20:21], v[20:21], v[18:19]
	v_mov_b32_e32 v20, v7
	v_mov_b32_e32 v21, v3
	v_pk_fma_f32 v[18:19], v[20:21], v[20:21], v[18:19]
	v_add_f32_e32 v16, v19, v16
	v_add_f32_e32 v16, v18, v16
	ds_bpermute_b32 v17, v180, v16
	s_nop 1
	v_mov_b32_dpp v202, v26 row_ror:8 row_mask:0xf bank_mask:0xf
	v_mov_b32_dpp v203, v27 row_ror:8 row_mask:0xf bank_mask:0xf
	v_mov_b32_e32 v210, 32
	v_mov_b32_e32 v211, 0
	v_mov_b32_e32 v206, v26
	v_mov_b32_e32 v207, v27
	v_lshl_add_u64 v[208:209], v[26:27], 0, v[210:211]
	v_lshl_add_u64 v[204:205], v[202:203], 0, v[210:211]
	v_mov_b32_dpp v212, v28 row_ror:8 row_mask:0xf bank_mask:0x3
	v_mov_b32_dpp v213, v29 row_ror:8 row_mask:0xf bank_mask:0x3
	v_mov_b32_dpp v214, v30 row_ror:8 row_mask:0xf bank_mask:0x3
	v_mov_b32_dpp v215, v31 row_ror:8 row_mask:0xf bank_mask:0x3
	v_mov_b32_dpp v206, v204 quad_perm:[0,1,2,3] row_mask:0xf bank_mask:0xc
	v_mov_b32_dpp v207, v205 quad_perm:[0,1,2,3] row_mask:0xf bank_mask:0xc
	v_mov_b32_dpp v208, v202 quad_perm:[0,1,2,3] row_mask:0xf bank_mask:0x3
	v_mov_b32_dpp v209, v203 quad_perm:[0,1,2,3] row_mask:0xf bank_mask:0x3
	v_mov_b32_dpp v28, v22 row_ror:8 row_mask:0xf bank_mask:0xc
	v_mov_b32_dpp v29, v23 row_ror:8 row_mask:0xf bank_mask:0xc
	v_mov_b32_dpp v30, v24 row_ror:8 row_mask:0xf bank_mask:0xc
	v_mov_b32_dpp v31, v25 row_ror:8 row_mask:0xf bank_mask:0xc
	v_mov_b32_dpp v22, v212 quad_perm:[0,1,2,3] row_mask:0xf bank_mask:0x3
	v_mov_b32_dpp v23, v213 quad_perm:[0,1,2,3] row_mask:0xf bank_mask:0x3
	v_mov_b32_dpp v24, v214 quad_perm:[0,1,2,3] row_mask:0xf bank_mask:0x3
	v_mov_b32_dpp v25, v215 quad_perm:[0,1,2,3] row_mask:0xf bank_mask:0x3
	global_store_dwordx4 v[206:207], v[28:31], off
	global_store_dwordx4 v[208:209], v[22:25], off
	s_nop 1
	s_waitcnt lgkmcnt(0)
	v_add_f32_e32 v16, v16, v17
	ds_bpermute_b32 v17, v181, v16
	s_waitcnt lgkmcnt(0)
	v_add_f32_e32 v16, v16, v17
	v_fmamk_f32 v16, v16, 0x3c800000, v250
	v_cmp_gt_f32_e32 vcc, s21, v16
	v_mul_f32_e32 v17, 0x4b800000, v16
	s_nop 0
	v_cndmask_b32_e32 v16, v16, v17, vcc
	v_rsq_f32_e32 v16, v16
	s_nop 0
	v_mul_f32_e32 v17, 0x45800000, v16
	v_cndmask_b32_e32 v16, v16, v17, vcc
	v_pk_mul_f32 v[12:13], v[12:13], v[16:17] op_sel_hi:[1,0]
	v_pk_mul_f32 v[14:15], v[14:15], v[16:17] op_sel_hi:[1,0]
	v_pk_mul_f32 v[8:9], v[8:9], v[16:17] op_sel_hi:[1,0]
	v_pk_mul_f32 v[10:11], v[10:11], v[16:17] op_sel_hi:[1,0]
	v_pk_mul_f32 v[0:1], v[0:1], v[16:17] op_sel_hi:[1,0]
	v_pk_mul_f32 v[2:3], v[2:3], v[16:17] op_sel_hi:[1,0]
	v_pk_mul_f32 v[4:5], v[4:5], v[16:17] op_sel_hi:[1,0]
	v_pk_mul_f32 v[6:7], v[6:7], v[16:17] op_sel_hi:[1,0]
	v_pk_mul_f32 v[14:15], v[78:79], v[14:15]
	v_pk_mul_f32 v[12:13], v[76:77], v[12:13]
	v_pk_mul_f32 v[10:11], v[70:71], v[10:11]
	v_pk_mul_f32 v[8:9], v[68:69], v[8:9]
	v_pk_mul_f32 v[2:3], v[74:75], v[2:3]
	v_pk_mul_f32 v[0:1], v[72:73], v[0:1]
	v_pk_mul_f32 v[6:7], v[66:67], v[6:7]
	v_pk_mul_f32 v[4:5], v[64:65], v[4:5]
	s_and_b64 vcc, exec, s[4:5]
	s_cbranch_vccnz .LBB0_768
	v_add_u32_e32 v16, s20, v164
	v_lshrrev_b32_e32 v16, 6, v16
	v_cndmask_b32_e64 v16, v184, v16, s[44:45]
	v_lshlrev_b32_e32 v32, 7, v16
	v_add_u32_e32 v20, v185, v32
	ds_read_b128 v[16:19], v20
	ds_read_b128 v[20:23], v20 offset:16
	s_waitcnt lgkmcnt(1)
	v_mov_b32_e32 v26, v17
	v_mov_b32_e32 v27, v19
	v_pk_mul_f32 v[28:29], v[0:1], v[26:27]
	s_waitcnt lgkmcnt(0)
	v_mov_b32_e32 v30, v21
	v_mov_b32_e32 v31, v23
	v_mov_b32_e32 v21, v22
	v_mov_b32_e32 v17, v18
	v_pk_mul_f32 v[24:25], v[2:3], v[30:31]
	v_pk_fma_f32 v[22:23], v[12:13], v[16:17], v[28:29] neg_lo:[0,0,1] neg_hi:[0,0,1]
	v_pk_mul_f32 v[0:1], v[0:1], v[16:17]
	v_pk_mul_f32 v[2:3], v[2:3], v[20:21]
	v_add_u32_e32 v16, v186, v32
	v_pk_fma_f32 v[24:25], v[14:15], v[20:21], v[24:25] neg_lo:[0,0,1] neg_hi:[0,0,1]
	v_pk_fma_f32 v[2:3], v[14:15], v[30:31], v[2:3]
	v_pk_fma_f32 v[0:1], v[12:13], v[26:27], v[0:1]
	ds_read_b128 v[12:15], v16
	ds_read_b128 v[16:19], v16 offset:16
	s_waitcnt lgkmcnt(1)
	v_mov_b32_e32 v26, v13
	v_mov_b32_e32 v27, v15
	v_pk_mul_f32 v[28:29], v[4:5], v[26:27]
	s_waitcnt lgkmcnt(0)
	v_mov_b32_e32 v30, v17
	v_mov_b32_e32 v31, v19
	v_mov_b32_e32 v17, v18
	v_mov_b32_e32 v13, v14
	v_pk_mul_f32 v[20:21], v[6:7], v[30:31]
	v_pk_fma_f32 v[18:19], v[8:9], v[12:13], v[28:29] neg_lo:[0,0,1] neg_hi:[0,0,1]
	v_pk_mul_f32 v[4:5], v[4:5], v[12:13]
	v_pk_mul_f32 v[6:7], v[6:7], v[16:17]
	v_pk_fma_f32 v[20:21], v[10:11], v[16:17], v[20:21] neg_lo:[0,0,1] neg_hi:[0,0,1]
	v_pk_fma_f32 v[6:7], v[10:11], v[30:31], v[6:7]
	v_pk_fma_f32 v[4:5], v[8:9], v[26:27], v[4:5]
	v_mov_b64_e32 v[8:9], v[18:19]
	v_mov_b64_e32 v[12:13], v[22:23]
	v_mov_b64_e32 v[10:11], v[20:21]
	v_mov_b64_e32 v[14:15], v[24:25]
